# v096 + P5 first 8 parameter slices loaded once into v216-247 (per-row reloads replaced by register copies)
# baseline (speedup 1.0000x reference)
; __device__ __forceinline__ float bf_lo(unsigned u) { return __uint_as_float(u << 16); }
; __device__ __forceinline__ float bf_hi(unsigned u) { return __uint_as_float(u & 0xffff0000u); }
; __device__ __forceinline__ unsigned pk2(float lo, float hi) { return pg8::cvt_pk_bf16(lo, hi); }
; __global__ void __launch_bounds__(NT, 2) mk_fwd(Args args) {
;     ...
;         for (int t_ = gw; t_ < MTOK * RMUL(5); t_ += NGW) { const int t = t_ & (MTOK - 1);
;             const size_t o = (size_t)t * 1024 + lane * 16;
;             f32x4 y[4];
; #pragma unroll
;             for (int j = 0; j < 4; ++j) y[j] = *(const f32x4*)(Y + o + 4 * j);
;             float s = 0.f;
; #pragma unroll
;             for (int j = 0; j < 4; ++j) s += (y[j].x + y[j].y) + (y[j].z + y[j].w);
;             s = quad_sum(s); const float mean = s * (1.0f / 64.0f);
;             float s2 = 0.f;
; #pragma unroll
;             for (int j = 0; j < 4; ++j) { y[j] = y[j] - mean; s2 += (y[j].x * y[j].x + y[j].y * y[j].y) + (y[j].z * y[j].z + y[j].w * y[j].w); }
;             s2 = quad_sum(s2); const float rstd = rsqrtf(s2 * (1.0f / 64.0f) + 64e-5f);
;             u32x4 r8[2], k8[2], v8[2], g8[2];
; #pragma unroll
;             for (int j = 0; j < 2; ++j) { r8[j] = *(const u32x4*)(RR + o + 8 * j); k8[j] = *(const u32x4*)(KP + o + 8 * j); v8[j] = *(const u32x4*)(VV + o + 8 * j); g8[j] = *(const u32x4*)(GG + o + 8 * j); }
;             float dp = 0.f;
; #pragma unroll
;             for (int j = 0; j < 2; ++j)
; #pragma unroll
;                 for (int e = 0; e < 4; ++e) { const int col = lane * 16 + j * 8 + e * 2; dp += bf_lo(r8[j][e]) * bf_lo(k8[j][e]) * rk[col] + bf_hi(r8[j][e]) * bf_hi(k8[j][e]) * rk[col + 1]; }
;             dp = quad_sum(dp);
;             u32x4 ov[2];
; #pragma unroll
;             for (int j = 0; j < 2; ++j)
; #pragma unroll
;                 for (int e = 0; e < 4; ++e) { const int c = j * 8 + e * 2; const int col = lane * 16 + c;
;                     const float y0 = y[c >> 2][c & 3], y1 = y[(c + 1) >> 2][(c + 1) & 3];
;                     const float o0 = (y0 * rstd * lng[col] + lnb[col] + dp * bf_lo(v8[j][e])) * bf_lo(g8[j][e]);
;                     const float o1 = (y1 * rstd * lng[col + 1] + lnb[col + 1] + dp * bf_hi(v8[j][e])) * bf_hi(g8[j][e]);
;                     ov[j][e] = pk2(o0, o1); }
.LBB0_506:
	s_cmp_lt_i32 s94, 6
	s_cselect_b64 s[0:1], -1, 0
	s_and_b64 s[0:1], s[0:1], s[6:7]
	s_and_b64 s[6:7], s[0:1], s[86:87]
	s_andn2_b64 vcc, exec, s[6:7]
	v_lshlrev_b32_e32 v136, 6, v128
	v_lshlrev_b32_e32 v138, 5, v128
	s_cbranch_vccnz .LBB0_509
	v_readlane_b32 s40, v249, 8
	v_readlane_b32 s48, v249, 16
	v_readlane_b32 s49, v249, 17
	v_mov_b32_e32 v137, 0
	v_readlane_b32 s46, v249, 14
	v_readlane_b32 s47, v249, 15
	v_readlane_b32 s50, v249, 18
	v_readlane_b32 s51, v249, 19
	s_mov_b64 s[8:9], s[48:49]
	v_mbcnt_hi_u32_b32 v61, -1, v169
	s_mov_b64 s[10:11], s[50:51]
	s_mov_b64 s[6:7], s[46:47]
	v_mov_b32_e32 v139, v137
	s_waitcnt vmcnt(0)
	v_and_b32_e32 v0, 64, v61
	v_lshl_add_u64 v[48:49], s[6:7], 0, v[136:137]
	v_lshl_add_u64 v[50:51], s[8:9], 0, v[136:137]
	v_lshl_add_u64 v[52:53], s[10:11], 0, v[136:137]
	v_lshl_add_u64 v[54:55], s[56:57], 0, v[136:137]
	v_lshl_add_u64 v[56:57], s[80:81], 0, v[138:139]
	s_mov_b32 s7, 0
	v_mov_b32_e32 v60, 0x3a27c5ac
	s_mov_b32 s3, 0x800000
	v_xor_b32_e32 v62, 16, v61
	v_add_u32_e32 v63, 64, v0
	v_xor_b32_e32 v64, 32, v61
	v_mov_b32_e32 v65, 0x358637bd
	s_mov_b32 s8, s70
	v_readlane_b32 s41, v249, 9
	v_readlane_b32 s42, v249, 10
	v_readlane_b32 s43, v249, 11
	v_readlane_b32 s44, v249, 12
	v_readlane_b32 s45, v249, 13
	v_readlane_b32 s52, v249, 20
	v_readlane_b32 s53, v249, 21
	v_readlane_b32 s54, v249, 22
	v_readlane_b32 s55, v249, 23
	global_load_dwordx4 v[200:203], v[54:55], off
	global_load_dwordx4 v[204:207], v[54:55], off offset:16
	global_load_dwordx4 v[208:211], v[54:55], off offset:32
	global_load_dwordx4 v[212:215], v[54:55], off offset:48
	s_waitcnt vmcnt(0)
	global_load_dwordx4 v[216:219], v[48:49], off offset:48
	global_load_dwordx4 v[220:223], v[48:49], off offset:32
	global_load_dwordx4 v[224:227], v[48:49], off offset:16
	global_load_dwordx4 v[228:231], v[48:49], off
	global_load_dwordx4 v[232:235], v[50:51], off
	global_load_dwordx4 v[244:247], v[50:51], off offset:16
	global_load_dwordx4 v[236:239], v[52:53], off
	global_load_dwordx4 v[240:243], v[52:53], off offset:16
	s_waitcnt vmcnt(0)
.LBB0_508:
	s_and_b32 s6, s8, 0x3fff
	v_cmp_lt_i32_e32 vcc, v62, v63
	v_lshl_or_b32 v66, s6, 10, v130
	s_lshl_b32 s6, s6, 12
	v_cndmask_b32_e32 v58, v61, v62, vcc
	v_cmp_lt_i32_e32 vcc, v64, v63
	v_lshlrev_b32_e32 v114, 2, v66
	v_lshlrev_b32_e32 v115, 1, v66
	v_cndmask_b32_e32 v59, v61, v64, vcc
	v_mov_b32_e32 v0, v216
	v_mov_b32_e32 v1, v217
	v_mov_b32_e32 v2, v218
	v_mov_b32_e32 v3, v219
	v_mov_b32_e32 v4, v220
	v_mov_b32_e32 v5, v221
	v_mov_b32_e32 v6, v222
	v_mov_b32_e32 v7, v223
	v_mov_b32_e32 v8, v224
	v_mov_b32_e32 v9, v225
	v_mov_b32_e32 v10, v226
	v_mov_b32_e32 v11, v227
	v_mov_b32_e32 v12, v228
	v_mov_b32_e32 v13, v229
	v_mov_b32_e32 v14, v230
	v_mov_b32_e32 v15, v231
	v_mov_b32_e32 v16, v232
	v_mov_b32_e32 v17, v233
	v_mov_b32_e32 v18, v234
	v_mov_b32_e32 v19, v235
	v_mov_b32_e32 v20, v236
	v_mov_b32_e32 v21, v237
	v_mov_b32_e32 v22, v238
	v_mov_b32_e32 v23, v239
	v_mov_b32_e32 v24, v240
	v_mov_b32_e32 v25, v241
	v_mov_b32_e32 v26, v242
	v_mov_b32_e32 v27, v243
	v_mov_b32_e32 v28, v244
	v_mov_b32_e32 v29, v245
	v_mov_b32_e32 v30, v246
	v_mov_b32_e32 v31, v247
	global_load_dwordx4 v[36:39], v[50:51], off offset:32
	global_load_dwordx4 v[40:43], v[50:51], off offset:48
	global_load_dwordx4 v[44:47], v[52:53], off offset:32
	global_load_dwordx4 v[32:35], v[52:53], off offset:48
	v_lshlrev_b32_e32 v129, 2, v58
	v_lshlrev_b32_e32 v131, 2, v59
	v_lshl_add_u64 v[58:59], v[56:57], 0, s[6:7]
	global_load_dwordx4 v[66:69], v114, s[20:21]
	global_load_dwordx4 v[70:73], v114, s[20:21] offset:16
	global_load_dwordx4 v[74:77], v114, s[20:21] offset:32
	global_load_dwordx4 v[78:81], v114, s[20:21] offset:48
	global_load_dwordx4 v[82:85], v115, s[28:29]
	global_load_dwordx4 v[86:89], v115, s[96:97]
	global_load_dwordx4 v[90:93], v115, s[28:29] offset:16
	global_load_dwordx4 v[94:97], v115, s[96:97] offset:16
	global_load_dwordx4 v[98:101], v115, s[24:25]
	global_load_dwordx4 v[102:105], v115, s[26:27]
	global_load_dwordx4 v[106:109], v115, s[24:25] offset:16
	global_load_dwordx4 v[110:113], v115, s[26:27] offset:16
	s_nop 0
	global_load_dwordx4 v[114:117], v[58:59], off offset:16
	global_load_dwordx4 v[118:121], v[58:59], off
	s_add_i32 s8, s8, s72
	s_cmpk_lt_i32 s8, 0x4000
	s_waitcnt vmcnt(13)
	v_mov_b32_e32 v142, v66
	v_mov_b32_e32 v143, v69
	s_waitcnt vmcnt(12)
	v_mov_b32_e32 v144, v71
	v_mov_b32_e32 v122, v13
	v_mov_b32_e32 v123, v14
	v_mov_b32_e32 v13, v15
	v_mov_b32_e32 v14, v67
	v_mov_b32_e32 v15, v68
	v_mov_b32_e32 v145, v72
	v_mov_b32_e32 v146, v70
	v_mov_b32_e32 v147, v73
	v_mov_b32_e32 v140, v1
	v_mov_b32_e32 v1, v3
	s_waitcnt vmcnt(9)
	v_and_b32_e32 v154, 0xffff0000, v82
	v_lshlrev_b32_e32 v155, 16, v83
	s_waitcnt vmcnt(8)
	v_and_b32_e32 v156, 0xffff0000, v86
	v_lshlrev_b32_e32 v157, 16, v87
	v_lshlrev_b32_e32 v82, 16, v82
	v_and_b32_e32 v83, 0xffff0000, v83
	v_lshlrev_b32_e32 v86, 16, v86
	v_and_b32_e32 v87, 0xffff0000, v87
	s_waitcnt vmcnt(5)
	v_lshlrev_b32_e32 v137, 16, v99
	v_and_b32_e32 v172, 0xffff0000, v99
	s_waitcnt vmcnt(3)
	v_lshlrev_b32_e32 v190, 16, v108
	v_and_b32_e32 v192, 0xffff0000, v108
	v_lshlrev_b32_e32 v99, 16, v109
	v_and_b32_e32 v3, 0xffff0000, v109
	v_pk_add_f32 v[14:15], v[14:15], v[142:143]
	v_pk_add_f32 v[108:109], v[144:145], v[146:147]
	v_mov_b32_e32 v126, v5
	v_mov_b32_e32 v5, v7
	v_pk_mul_f32 v[82:83], v[82:83], v[86:87]
	v_add_f32_e32 v7, v14, v15
	v_pk_add_f32 v[14:15], v[108:109], v[108:109] op_sel:[0,1] op_sel_hi:[1,0]
	v_add_f32_e32 v148, v74, v75
	v_add_f32_e32 v150, v76, v77
	v_mov_b32_e32 v153, v78
	v_mov_b32_e32 v149, v80
	v_mov_b32_e32 v151, v81
	v_and_b32_e32 v158, 0xffff0000, v84
	v_lshlrev_b32_e32 v159, 16, v85
	v_and_b32_e32 v160, 0xffff0000, v88
	v_lshlrev_b32_e32 v161, 16, v89
	v_lshlrev_b32_e32 v84, 16, v84
	v_and_b32_e32 v85, 0xffff0000, v85
	v_lshlrev_b32_e32 v88, 16, v88
	v_and_b32_e32 v89, 0xffff0000, v89
	s_waitcnt vmcnt(2)
; __device__ __forceinline__ float bf_lo(unsigned u) { return __uint_as_float(u << 16); }
; __device__ __forceinline__ float bf_hi(unsigned u) { return __uint_as_float(u & 0xffff0000u); }
; __device__ __forceinline__ unsigned pk2(float lo, float hi) { return pg8::cvt_pk_bf16(lo, hi); }
; __device__ __forceinline__ float quad_sum(float v) { v += dpp_mov<0xB1>(v); v += dpp_mov<0x4E>(v); return v; }
; __global__ void __launch_bounds__(NT, 2) mk_fwd(Args args) {
;     ...
;             s = quad_sum(s); const float mean = s * (1.0f / 64.0f);
;             float s2 = 0.f;
; #pragma unroll
;             for (int j = 0; j < 4; ++j) { y[j] = y[j] - mean; s2 += (y[j].x * y[j].x + y[j].y * y[j].y) + (y[j].z * y[j].z + y[j].w * y[j].w); }
;             s2 = quad_sum(s2); const float rstd = rsqrtf(s2 * (1.0f / 64.0f) + 64e-5f);
;             u32x4 r8[2], k8[2], v8[2], g8[2];
; #pragma unroll
;             for (int j = 0; j < 2; ++j) { r8[j] = *(const u32x4*)(RR + o + 8 * j); k8[j] = *(const u32x4*)(KP + o + 8 * j); v8[j] = *(const u32x4*)(VV + o + 8 * j); g8[j] = *(const u32x4*)(GG + o + 8 * j); }
;             float dp = 0.f;
; #pragma unroll
;             for (int j = 0; j < 2; ++j)
; #pragma unroll
;                 for (int e = 0; e < 4; ++e) { const int col = lane * 16 + j * 8 + e * 2; dp += bf_lo(r8[j][e]) * bf_lo(k8[j][e]) * rk[col] + bf_hi(r8[j][e]) * bf_hi(k8[j][e]) * rk[col + 1]; }
;             dp = quad_sum(dp);
;             u32x4 ov[2];
; #pragma unroll
;             for (int j = 0; j < 2; ++j)
; #pragma unroll
;                 for (int e = 0; e < 4; ++e) { const int c = j * 8 + e * 2; const int col = lane * 16 + c;
;                     const float y0 = y[c >> 2][c & 3], y1 = y[(c + 1) >> 2][(c + 1) & 3];
;                     const float o0 = (y0 * rstd * lng[col] + lnb[col] + dp * bf_lo(v8[j][e])) * bf_lo(g8[j][e]);
;                     const float o1 = (y1 * rstd * lng[col + 1] + lnb[col + 1] + dp * bf_hi(v8[j][e])) * bf_hi(g8[j][e]);
;                     ov[j][e] = pk2(o0, o1); }
	v_lshlrev_b32_e32 v191, 16, v112
	v_and_b32_e32 v193, 0xffff0000, v112
	v_lshlrev_b32_e32 v194, 16, v113
	v_and_b32_e32 v195, 0xffff0000, v113
	v_pk_mul_f32 v[112:113], v[154:155], v[156:157]
	v_pk_mul_f32 v[12:13], v[12:13], v[82:83]
	v_add_f32_e32 v152, 0, v7
	v_mov_b32_e32 v15, v79
	v_mov_b32_e32 v124, v9
	v_mov_b32_e32 v9, v11
	v_lshlrev_b32_e32 v183, 16, v110
	v_and_b32_e32 v185, 0xffff0000, v110
	v_lshlrev_b32_e32 v187, 16, v111
	v_and_b32_e32 v189, 0xffff0000, v111
	v_pk_add_f32 v[110:111], v[148:149], v[150:151]
	v_pk_mul_f32 v[84:85], v[84:85], v[88:89]
	v_pk_fma_f32 v[12:13], v[122:123], v[112:113], v[12:13]
	v_pk_add_f32 v[14:15], v[152:153], v[14:15]
	v_mov_b32_e32 v125, v10
	v_and_b32_e32 v162, 0xffff0000, v90
	v_lshlrev_b32_e32 v163, 16, v91
	v_and_b32_e32 v164, 0xffff0000, v94
	v_lshlrev_b32_e32 v165, 16, v95
	v_lshlrev_b32_e32 v90, 16, v90
	v_and_b32_e32 v91, 0xffff0000, v91
	v_lshlrev_b32_e32 v94, 16, v94
	v_and_b32_e32 v95, 0xffff0000, v95
	v_pk_mul_f32 v[86:87], v[158:159], v[160:161]
	v_pk_mul_f32 v[8:9], v[8:9], v[84:85]
	v_add_f32_e32 v7, 0, v12
	v_pk_add_f32 v[14:15], v[14:15], v[110:111]
	v_pk_mul_f32 v[90:91], v[90:91], v[94:95]
	v_pk_fma_f32 v[8:9], v[124:125], v[86:87], v[8:9]
	v_add_f32_e32 v7, v7, v13
	v_add_f32_e32 v12, v14, v15
	v_mov_b32_e32 v127, v6
	v_and_b32_e32 v166, 0xffff0000, v92
	v_lshlrev_b32_e32 v167, 16, v93
	v_and_b32_e32 v170, 0xffff0000, v96
	v_lshlrev_b32_e32 v171, 16, v97
	v_lshlrev_b32_e32 v92, 16, v92
	v_and_b32_e32 v93, 0xffff0000, v93
	v_lshlrev_b32_e32 v96, 16, v96
	v_and_b32_e32 v97, 0xffff0000, v97
	v_pk_mul_f32 v[88:89], v[162:163], v[164:165]
	v_pk_mul_f32 v[4:5], v[4:5], v[90:91]
	v_add_f32_e32 v7, v7, v8
	v_add_f32_dpp v8, v12, v12 quad_perm:[1,0,3,2] row_mask:0xf bank_mask:0xf bound_ctrl:1
	v_mov_b32_e32 v10, v17
	v_pk_mul_f32 v[92:93], v[92:93], v[96:97]
	v_pk_fma_f32 v[4:5], v[126:127], v[88:89], v[4:5]
	v_add_f32_e32 v7, v7, v9
	v_add_f32_dpp v17, v8, v8 quad_perm:[2,3,0,1] row_mask:0xf bank_mask:0xf bound_ctrl:1
	v_mov_b32_e32 v141, v2
	v_pk_mul_f32 v[94:95], v[166:167], v[170:171]
	v_pk_mul_f32 v[0:1], v[0:1], v[92:93]
	v_add_f32_e32 v4, v7, v4
	v_fmamk_f32 v9, v17, 0xbc800000, v67
	v_fmamk_f32 v8, v17, 0xbc800000, v66
	v_fmamk_f32 v69, v17, 0xbc800000, v69
	v_fmac_f32_e32 v68, 0xbc800000, v17
	v_fmamk_f32 v13, v17, 0xbc800000, v71
	v_fmamk_f32 v12, v17, 0xbc800000, v70
	v_fmamk_f32 v73, v17, 0xbc800000, v73
	v_fmac_f32_e32 v72, 0xbc800000, v17
	v_pk_fma_f32 v[0:1], v[140:141], v[94:95], v[0:1]
	v_fmamk_f32 v15, v17, 0xbc800000, v75
	v_fmamk_f32 v14, v17, 0xbc800000, v74
	v_add_f32_e32 v7, v4, v5
	v_pk_mul_f32 v[4:5], v[68:69], v[68:69]
	v_pk_mul_f32 v[66:67], v[8:9], v[8:9]
	v_pk_mul_f32 v[70:71], v[72:73], v[72:73]
	v_pk_mul_f32 v[74:75], v[12:13], v[12:13]
	v_fmamk_f32 v77, v17, 0xbc800000, v77
	v_add_f32_e32 v0, v7, v0
	v_pk_mov_b32 v[82:83], v[66:67], v[4:5] op_sel:[1,0]
	v_mov_b32_e32 v67, v5
	v_pk_mov_b32 v[4:5], v[74:75], v[70:71] op_sel:[1,0]
	v_mov_b32_e32 v75, v71
	v_mov_b32_e32 v6, v20
	v_fmac_f32_e32 v76, 0xbc800000, v17
	v_fmamk_f32 v84, v17, 0xbc800000, v81
	v_fmamk_f32 v85, v17, 0xbc800000, v80
	v_fmamk_f32 v79, v17, 0xbc800000, v79
	v_fmac_f32_e32 v78, 0xbc800000, v17
	v_mul_f32_e32 v20, v15, v15
	v_mul_f32_e32 v80, v77, v77
	v_add_f32_e32 v7, v0, v1
	v_pk_add_f32 v[0:1], v[82:83], v[66:67]
	v_pk_add_f32 v[4:5], v[4:5], v[74:75]
	v_mul_f32_e32 v86, v78, v78
	v_mul_f32_e32 v87, v79, v79
	v_mul_f32_e32 v17, v85, v85
	v_mul_f32_e32 v88, v84, v84
	v_pk_fma_f32 v[70:71], v[14:15], v[14:15], v[20:21] op_sel_hi:[1,1,0]
	v_pk_fma_f32 v[80:81], v[76:77], v[76:77], v[80:81] op_sel_hi:[1,1,0]
	v_pk_add_f32 v[0:1], v[0:1], v[0:1] op_sel:[0,1] op_sel_hi:[1,0]
	v_pk_add_f32 v[4:5], v[4:5], v[4:5] op_sel:[0,1] op_sel_hi:[1,0]
	v_mov_b32_e32 v71, v17
	v_mov_b32_e32 v81, v88
	v_mov_b32_e32 v1, v86
	v_mov_b32_e32 v5, v87
	v_pk_add_f32 v[66:67], v[70:71], v[80:81]
	v_pk_add_f32 v[0:1], v[0:1], v[4:5]
	v_add_f32_dpp v17, v7, v7 quad_perm:[1,0,3,2] row_mask:0xf bank_mask:0xf bound_ctrl:1
	v_pk_add_f32 v[0:1], v[0:1], v[66:67]
	v_mov_b32_e32 v2, v43
	v_add_f32_e32 v0, v0, v1
	v_mov_b32_dpp v7, v17 quad_perm:[2,3,0,1] row_mask:0xf bank_mask:0xf bound_ctrl:1
	v_lshlrev_b32_e32 v43, 16, v98
	v_add_f32_dpp v0, v0, v0 quad_perm:[1,0,3,2] row_mask:0xf bank_mask:0xf bound_ctrl:1
	v_and_b32_e32 v176, 0xffff0000, v100
	v_lshlrev_b32_e32 v178, 16, v101
	v_add_f32_dpp v0, v0, v0 quad_perm:[2,3,0,1] row_mask:0xf bank_mask:0xf bound_ctrl:1
	v_fmamk_f32 v0, v0, 0x3c800000, v60
	v_mul_f32_e32 v1, 0x4b800000, v0
	v_cmp_gt_f32_e32 vcc, s3, v0
	v_lshlrev_b32_e32 v182, 16, v106
	v_lshlrev_b32_e32 v133, 16, v102
	v_cndmask_b32_e32 v0, v0, v1, vcc
	v_rsq_f32_e32 v0, v0
	v_and_b32_e32 v11, 0xffff0000, v98
	v_lshlrev_b32_e32 v139, 16, v103
	v_and_b32_e32 v173, 0xffff0000, v103
	v_mul_f32_e32 v1, 0x45800000, v0
	v_cndmask_b32_e32 v4, v0, v1, vcc
	v_mul_f32_e32 v0, v4, v8
	v_mul_f32_e32 v1, v4, v68
	v_mul_f32_e32 v5, v4, v69
	v_mul_f32_e32 v8, v4, v12
	v_mul_f32_e32 v12, v4, v13
	v_mul_f32_e32 v13, v4, v72
	v_mul_f32_e32 v14, v4, v14
	v_mul_f32_e32 v16, v16, v0
	v_mul_f32_e32 v20, v4, v73
	v_mul_f32_e32 v15, v4, v15
	v_fma_f32 v18, v18, v1, v22
	v_fmac_f32_e32 v23, v5, v19
	v_fma_f32 v5, v28, v8, v24
	v_fma_f32 v8, v12, v29, v25
	v_fma_f32 v12, v30, v13, v26
	v_fma_f32 v13, v36, v14, v44
	v_pk_add_f32 v[0:1], v[6:7], v[16:17]
	v_lshlrev_b32_e32 v174, 16, v100
	v_and_b32_e32 v177, 0xffff0000, v104
	v_lshlrev_b32_e32 v179, 16, v105
	v_and_b32_e32 v180, 0xffff0000, v101
	v_and_b32_e32 v184, 0xffff0000, v106
	v_fmac_f32_e32 v27, v20, v31
	v_fma_f32 v14, v15, v37, v45
	v_fma_f32 v6, v1, v43, v0
; __device__ __forceinline__ float bf_lo(unsigned u) { return __uint_as_float(u << 16); }
; __device__ __forceinline__ float bf_hi(unsigned u) { return __uint_as_float(u & 0xffff0000u); }
; __device__ __forceinline__ unsigned pk2(float lo, float hi) { return pg8::cvt_pk_bf16(lo, hi); }
; __device__ __forceinline__ float wave_sum(float v) { v = row16_sum(v); v += __shfl_xor(v, 16); v += __shfl_xor(v, 32); return v; }
; __global__ void __launch_bounds__(NT, 2) mk_fwd(Args args) {
;     ...
;                     const float o0 = (y0 * rstd * lng[col] + lnb[col] + dp * bf_lo(v8[j][e])) * bf_lo(g8[j][e]);
;                     const float o1 = (y1 * rstd * lng[col + 1] + lnb[col + 1] + dp * bf_hi(v8[j][e])) * bf_hi(g8[j][e]);
;                     ov[j][e] = pk2(o0, o1); }
;             bf16* op = HB + (size_t)t * DM + 1024 + lane * 16;
;             *(u32x4*)op = ov[0]; *(u32x4*)(op + 8) = ov[1];
;             {
;                 bf16* ap = HB + (size_t)t * DM + lane * 16; u32x4 ya[2]; ya[0] = *(const u32x4*)ap; ya[1] = *(const u32x4*)(ap + 8);
;                 float q2 = 0.f;
; #pragma unroll
;                 for (int j = 0; j < 2; ++j)
; #pragma unroll
;                     for (int e = 0; e < 4; ++e) { const float v0 = bf_lo(ya[j][e]), v1 = bf_hi(ya[j][e]); q2 += v0 * v0 + v1 * v1; }
;                 q2 = wave_sum(q2);
;                 const float ri = rsqrtf(q2 * (1.0f / 1024.0f) + 1e-6f);
; #pragma unroll
;                 for (int j = 0; j < 2; ++j)
; #pragma unroll
;                     for (int e = 0; e < 4; ++e) { const int col = lane * 16 + j * 8 + e * 2; ya[j][e] = pk2(bf_lo(ya[j][e]) * ri * og[col], bf_hi(ya[j][e]) * ri * og[col + 1]); }
;                 *(u32x4*)ap = ya[0]; *(u32x4*)(ap + 8) = ya[1];
	v_mul_f32_e32 v0, v4, v9
	v_fmac_f32_e32 v18, v1, v137
	v_fmac_f32_e32 v23, v1, v172
	v_fmac_f32_e32 v8, v1, v176
	v_fmac_f32_e32 v12, v1, v178
	v_fmac_f32_e32 v13, v1, v182
	v_lshlrev_b32_e32 v175, 16, v104
	v_and_b32_e32 v181, 0xffff0000, v105
	v_mul_f32_e32 v66, v4, v76
	v_mul_f32_e32 v67, v4, v77
	v_mul_f32_e32 v68, v4, v78
	v_mul_f32_e32 v69, v4, v79
	v_mul_f32_e32 v98, v4, v85
	v_fmac_f32_e32 v5, v1, v174
	v_fmac_f32_e32 v27, v1, v180
	v_fmac_f32_e32 v14, v1, v184
	v_mul_f32_e32 v16, v6, v133
	v_pk_mul_f32 v[10:11], v[0:1], v[10:11]
	v_mul_f32_e32 v6, v18, v139
	v_mul_f32_e32 v7, v23, v173
	v_mul_f32_e32 v8, v8, v177
	v_mul_f32_e32 v12, v12, v179
	v_mul_f32_e32 v13, v13, v183
	v_mov_b32_e32 v0, v42
	v_lshlrev_b32_e32 v186, 16, v107
	v_and_b32_e32 v188, 0xffff0000, v107
	v_fma_f32 v15, v38, v66, v46
	v_fmac_f32_e32 v47, v67, v39
	v_fma_f32 v19, v40, v68, v32
	v_fma_f32 v20, v69, v41, v33
	v_mul_f32_e32 v9, v5, v175
	v_mul_f32_e32 v17, v27, v181
	v_mul_f32_e32 v14, v14, v185
	v_cvt_pk_bf16_f32 v5, v6, v7
	v_cvt_pk_bf16_f32 v6, v9, v8
	v_cvt_pk_bf16_f32 v7, v12, v17
	v_cvt_pk_bf16_f32 v8, v13, v14
	v_pk_mul_f32 v[12:13], v[0:1], v[98:99]
	v_mul_f32_e32 v0, v4, v84
	v_fmac_f32_e32 v15, v1, v186
	v_fmac_f32_e32 v47, v1, v188
	v_fmac_f32_e32 v19, v1, v190
	v_fmac_f32_e32 v20, v1, v192
	v_add_f32_e32 v21, v10, v21
	v_pk_mul_f32 v[0:1], v[0:1], v[2:3]
	v_and_b32_e32 v135, 0xffff0000, v102
	v_add_f32_e32 v4, v21, v11
	v_add_f32_e32 v11, v34, v12
	v_add_f32_e32 v0, v0, v35
	v_mul_f32_e32 v2, v4, v135
	v_add_f32_e32 v3, v11, v13
	v_add_f32_e32 v0, v0, v1
	v_mul_f32_e32 v15, v15, v187
	v_mul_f32_e32 v18, v47, v189
	v_mul_f32_e32 v19, v19, v191
	v_mul_f32_e32 v20, v20, v193
	v_cvt_pk_bf16_f32 v9, v15, v18
	v_cvt_pk_bf16_f32 v10, v19, v20
	v_cvt_pk_bf16_f32 v4, v16, v2
	v_mul_f32_e32 v2, v3, v194
	v_mul_f32_e32 v0, v0, v195
	global_store_dwordx4 v[58:59], v[4:7], off offset:2048
	v_cvt_pk_bf16_f32 v11, v2, v0
	global_store_dwordx4 v[58:59], v[8:11], off offset:2064
	v_mov_b32_e32 v0, v200
	v_mov_b32_e32 v1, v201
	v_mov_b32_e32 v2, v202
	v_mov_b32_e32 v3, v203
	v_mov_b32_e32 v4, v204
	v_mov_b32_e32 v5, v205
	v_mov_b32_e32 v6, v206
	v_mov_b32_e32 v7, v207
	s_nop 0
	v_mov_b32_e32 v8, v208
	v_mov_b32_e32 v9, v209
	v_mov_b32_e32 v10, v210
	v_mov_b32_e32 v11, v211
	v_mov_b32_e32 v12, v212
	v_mov_b32_e32 v13, v213
	v_mov_b32_e32 v14, v214
	v_mov_b32_e32 v15, v215
	s_waitcnt vmcnt(2)
	v_lshlrev_b32_e32 v196, 16, v118
	v_and_b32_e32 v118, 0xffff0000, v118
	v_lshlrev_b32_e32 v197, 16, v119
	v_and_b32_e32 v119, 0xffff0000, v119
	v_lshlrev_b32_e32 v198, 16, v120
	v_and_b32_e32 v120, 0xffff0000, v120
	v_lshlrev_b32_e32 v100, 16, v114
	v_lshlrev_b32_e32 v101, 16, v115
	v_and_b32_e32 v103, 0xffff0000, v115
	v_and_b32_e32 v102, 0xffff0000, v114
	v_mul_f32_e32 v114, v118, v118
	v_mul_f32_e32 v115, v119, v119
	v_lshlrev_b32_e32 v199, 16, v121
	v_and_b32_e32 v121, 0xffff0000, v121
	v_lshlrev_b32_e32 v104, 16, v116
	v_and_b32_e32 v106, 0xffff0000, v116
	v_mul_f32_e32 v116, v120, v120
	v_fmac_f32_e32 v114, v196, v196
	v_fmac_f32_e32 v115, v197, v197
	v_lshlrev_b32_e32 v105, 16, v117
	v_and_b32_e32 v107, 0xffff0000, v117
	v_mul_f32_e32 v117, v121, v121
	v_fmac_f32_e32 v116, v198, v198
	v_add_f32_e32 v20, v114, v115
	v_pk_mul_f32 v[96:97], v[102:103], v[102:103]
	v_fmac_f32_e32 v117, v199, v199
	v_add_f32_e32 v20, v20, v116
	v_pk_fma_f32 v[18:19], v[100:101], v[100:101], v[96:97]
	v_add_f32_e32 v20, v20, v117
	v_pk_mul_f32 v[16:17], v[106:107], v[106:107]
	v_add_f32_e32 v18, v20, v18
	v_pk_fma_f32 v[16:17], v[104:105], v[104:105], v[16:17]
	v_add_f32_e32 v18, v18, v19
	v_add_f32_e32 v16, v18, v16
	v_add_f32_e32 v16, v16, v17
	s_nop 1
	v_add_f32_dpp v16, v16, v16 quad_perm:[1,0,3,2] row_mask:0xf bank_mask:0xf bound_ctrl:1
	s_nop 1
	v_add_f32_dpp v16, v16, v16 quad_perm:[2,3,0,1] row_mask:0xf bank_mask:0xf bound_ctrl:1
	s_nop 1
	v_add_f32_dpp v16, v16, v16 row_half_mirror row_mask:0xf bank_mask:0xf bound_ctrl:1
	s_nop 1
	v_add_f32_dpp v16, v16, v16 row_mirror row_mask:0xf bank_mask:0xf bound_ctrl:1
	ds_bpermute_b32 v17, v129, v16
	s_waitcnt lgkmcnt(0)
	v_add_f32_e32 v16, v16, v17
	ds_bpermute_b32 v17, v131, v16
	s_waitcnt lgkmcnt(0)
	v_add_f32_e32 v16, v16, v17
	v_fmamk_f32 v16, v16, 0x3a800000, v65
	v_mul_f32_e32 v17, 0x4b800000, v16
	v_cmp_gt_f32_e32 vcc, s3, v16
	s_nop 1
	v_cndmask_b32_e32 v16, v16, v17, vcc
	v_rsq_f32_e32 v16, v16
	s_nop 0
	v_mul_f32_e32 v17, 0x45800000, v16
	v_cndmask_b32_e32 v16, v16, v17, vcc
	v_mul_f32_e32 v17, v16, v196
	v_mul_f32_e32 v18, v16, v118
	v_mul_f32_e32 v19, v16, v197
	v_mul_f32_e32 v20, v16, v119
	v_mul_f32_e32 v21, v16, v198
	v_mul_f32_e32 v22, v16, v120
	v_mul_f32_e32 v23, v16, v199
	v_mul_f32_e32 v24, v16, v121
	v_mul_f32_e32 v0, v0, v17
	v_mul_f32_e32 v1, v1, v18
	v_mul_f32_e32 v2, v2, v19
	v_mul_f32_e32 v3, v3, v20
	v_mul_f32_e32 v25, v16, v100
	v_mul_f32_e32 v26, v16, v102
	v_mul_f32_e32 v27, v16, v101
	v_mul_f32_e32 v28, v16, v103
	v_mul_f32_e32 v29, v16, v104
	v_mul_f32_e32 v30, v16, v106
	v_mul_f32_e32 v31, v16, v105
	v_mul_f32_e32 v16, v16, v107
	v_mul_f32_e32 v4, v4, v21
	v_mul_f32_e32 v5, v5, v22
	v_mul_f32_e32 v6, v6, v23
	v_mul_f32_e32 v7, v7, v24
	v_cvt_pk_bf16_f32 v0, v0, v1
	v_cvt_pk_bf16_f32 v1, v2, v3
	v_cvt_pk_bf16_f32 v2, v4, v5
	v_cvt_pk_bf16_f32 v3, v6, v7
	v_mul_f32_e32 v8, v8, v25
	v_mul_f32_e32 v9, v9, v26
	v_mul_f32_e32 v10, v10, v27
	v_mul_f32_e32 v11, v11, v28
	v_mul_f32_e32 v12, v12, v29
	v_mul_f32_e32 v13, v13, v30
	v_mul_f32_e32 v14, v14, v31
	v_mul_f32_e32 v15, v15, v16
	v_cvt_pk_bf16_f32 v4, v8, v9
	v_cvt_pk_bf16_f32 v5, v10, v11
	v_cvt_pk_bf16_f32 v6, v12, v13
	v_cvt_pk_bf16_f32 v7, v14, v15
	global_store_dwordx4 v[58:59], v[0:3], off
	global_store_dwordx4 v[58:59], v[4:7], off offset:16
	s_cbranch_scc1 .LBB0_508

; __device__ __forceinline__ void xcd_barrier(const XcdBarrier& b) {
;     asm volatile("s_waitcnt vmcnt(0)" ::: "memory");
;     __syncthreads();
.LBB0_562:
	s_or_b64 exec, exec, s[0:1]
	s_waitcnt lgkmcnt(0)
	s_barrier
	s_nop 0
	s_nop 0
	s_nop 0
	s_nop 0
	s_nop 0
	s_nop 0
	s_nop 0
	s_nop 0
	s_nop 0
	s_nop 0
	s_nop 0
	s_nop 0
	s_nop 0
	s_nop 0
	s_nop 0
	s_nop 0
	s_nop 0
	s_nop 0
